# grid barrier: per-XCC generation add removed from the leader tail (nobody polls it any more)
# speedup vs baseline: 1.0033x; 1.0033x over previous
; __device__ __forceinline__ unsigned xb_add(unsigned* p, unsigned v) { return __hip_atomic_fetch_add(p, v, __ATOMIC_RELAXED, __HIP_MEMORY_SCOPE_AGENT); }
; __device__ __forceinline__ void xcd_barrier(const XcdBarrier& b) {
;     ...
;             __builtin_amdgcn_fence(__ATOMIC_ACQUIRE, "agent");
;             xb_add(&bar[XB_XGEN(bx_)], 1u);
;             asm volatile("s_waitcnt vmcnt(0)" ::: "memory");
.LBB0_281:
	s_or_b64 exec, exec, s[4:5]
	s_mov_b64 s[4:5], exec
	v_mbcnt_lo_u32_b32 v1, s4, 0
	v_mbcnt_hi_u32_b32 v1, s5, v1
	v_cmp_eq_u32_e32 vcc, 0, v1
	s_waitcnt vmcnt(0)
	buffer_inv sc1
	s_and_saveexec_b64 s[6:7], vcc
	s_cbranch_execz .LBB0_283
	s_bcnt1_i32_b64 s4, s[4:5]
	v_mov_b32_e32 v1, 0x2000
	v_mov_b32_e32 v2, s4
.LBB0_283:
	s_or_b64 exec, exec, s[6:7]
	s_waitcnt vmcnt(0)

; __device__ __forceinline__ unsigned xb_add(unsigned* p, unsigned v) { return __hip_atomic_fetch_add(p, v, __ATOMIC_RELAXED, __HIP_MEMORY_SCOPE_AGENT); }
; __device__ __forceinline__ void xcd_barrier(const XcdBarrier& b) {
;     ...
;             __builtin_amdgcn_fence(__ATOMIC_ACQUIRE, "agent");
;             xb_add(&bar[XB_XGEN(bx_)], 1u);
;             asm volatile("s_waitcnt vmcnt(0)" ::: "memory");
.LBB0_541:
	s_or_b64 exec, exec, s[4:5]
	s_mov_b64 s[4:5], exec
	v_mbcnt_lo_u32_b32 v2, s4, 0
	v_mbcnt_hi_u32_b32 v2, s5, v2
	v_cmp_eq_u32_e32 vcc, 0, v2
	s_waitcnt vmcnt(0)
	buffer_inv sc1
	s_and_saveexec_b64 s[6:7], vcc
	s_cbranch_execz .LBB0_543
	s_bcnt1_i32_b64 s4, s[4:5]
	v_mov_b32_e32 v2, s4
	v_mov_b32_e32 v4, 0x2000
.LBB0_543:
	s_or_b64 exec, exec, s[6:7]
	s_waitcnt vmcnt(0)

; __device__ __forceinline__ unsigned xb_add(unsigned* p, unsigned v) { return __hip_atomic_fetch_add(p, v, __ATOMIC_RELAXED, __HIP_MEMORY_SCOPE_AGENT); }
; __device__ __forceinline__ void xcd_barrier(const XcdBarrier& b) {
;     ...
;             __builtin_amdgcn_fence(__ATOMIC_ACQUIRE, "agent");
;             xb_add(&bar[XB_XGEN(bx_)], 1u);
;             asm volatile("s_waitcnt vmcnt(0)" ::: "memory");
.LBB0_749:
	s_or_b64 exec, exec, s[4:5]
	s_mov_b64 s[4:5], exec
	v_mbcnt_lo_u32_b32 v2, s4, 0
	v_mbcnt_hi_u32_b32 v2, s5, v2
	v_cmp_eq_u32_e32 vcc, 0, v2
	s_waitcnt vmcnt(0)
	buffer_inv sc1
	s_and_saveexec_b64 s[6:7], vcc
	s_cbranch_execz .LBB0_547
	s_bcnt1_i32_b64 s4, s[4:5]
	v_mov_b32_e32 v2, s4
	v_mov_b32_e32 v4, 0x2000
	s_branch .LBB0_547

; __device__ __forceinline__ unsigned xb_add(unsigned* p, unsigned v) { return __hip_atomic_fetch_add(p, v, __ATOMIC_RELAXED, __HIP_MEMORY_SCOPE_AGENT); }
; __device__ __forceinline__ void xcd_barrier(const XcdBarrier& b) {
;     ...
;             __builtin_amdgcn_fence(__ATOMIC_ACQUIRE, "agent");
;             xb_add(&bar[XB_XGEN(bx_)], 1u);
;             asm volatile("s_waitcnt vmcnt(0)" ::: "memory");
.LBB0_801:
	s_or_b64 exec, exec, s[4:5]
	s_mov_b64 s[4:5], exec
	v_mbcnt_lo_u32_b32 v2, s4, 0
	v_mbcnt_hi_u32_b32 v2, s5, v2
	v_cmp_eq_u32_e32 vcc, 0, v2
	s_waitcnt vmcnt(0)
	buffer_inv sc1
	s_and_saveexec_b64 s[6:7], vcc
	s_cbranch_execz .LBB0_803
	s_bcnt1_i32_b64 s4, s[4:5]
	v_mov_b32_e32 v2, s4
	v_mov_b32_e32 v4, 0x2000
.LBB0_803:
	s_or_b64 exec, exec, s[6:7]
	s_waitcnt vmcnt(0)

; __device__ __forceinline__ unsigned xb_add(unsigned* p, unsigned v) { return __hip_atomic_fetch_add(p, v, __ATOMIC_RELAXED, __HIP_MEMORY_SCOPE_AGENT); }
; __device__ __forceinline__ void xcd_barrier(const XcdBarrier& b) {
;     ...
;             __builtin_amdgcn_fence(__ATOMIC_ACQUIRE, "agent");
;             xb_add(&bar[XB_XGEN(bx_)], 1u);
;             asm volatile("s_waitcnt vmcnt(0)" ::: "memory");
.LBB0_1235:
	s_or_b64 exec, exec, s[4:5]
	s_mov_b64 s[4:5], exec
	v_mbcnt_lo_u32_b32 v2, s4, 0
	v_mbcnt_hi_u32_b32 v2, s5, v2
	v_cmp_eq_u32_e32 vcc, 0, v2
	s_waitcnt vmcnt(0)
	buffer_inv sc1
	s_and_saveexec_b64 s[6:7], vcc
	s_cbranch_execz .LBB0_1237
	s_bcnt1_i32_b64 s4, s[4:5]
	v_mov_b32_e32 v2, s4
	v_mov_b32_e32 v4, 0x2000
.LBB0_1237:
	s_or_b64 exec, exec, s[6:7]
	s_waitcnt vmcnt(0)

; __device__ __forceinline__ unsigned xb_add(unsigned* p, unsigned v) { return __hip_atomic_fetch_add(p, v, __ATOMIC_RELAXED, __HIP_MEMORY_SCOPE_AGENT); }
; __device__ __forceinline__ void xcd_barrier(const XcdBarrier& b) {
;     ...
;             __builtin_amdgcn_fence(__ATOMIC_ACQUIRE, "agent");
;             xb_add(&bar[XB_XGEN(bx_)], 1u);
;             asm volatile("s_waitcnt vmcnt(0)" ::: "memory");
.LBB0_1294:
	s_or_b64 exec, exec, s[4:5]
	s_mov_b64 s[4:5], exec
	v_mbcnt_lo_u32_b32 v2, s4, 0
	v_mbcnt_hi_u32_b32 v2, s5, v2
	v_cmp_eq_u32_e32 vcc, 0, v2
	s_waitcnt vmcnt(0)
	buffer_inv sc1
	s_and_saveexec_b64 s[6:7], vcc
	s_cbranch_execz .LBB0_1296
	s_bcnt1_i32_b64 s4, s[4:5]
	v_mov_b32_e32 v2, s4
	v_mov_b32_e32 v4, 0x2000
.LBB0_1296:
	s_or_b64 exec, exec, s[6:7]
	s_waitcnt vmcnt(0)

; __device__ __forceinline__ unsigned xb_add(unsigned* p, unsigned v) { return __hip_atomic_fetch_add(p, v, __ATOMIC_RELAXED, __HIP_MEMORY_SCOPE_AGENT); }
; __device__ __forceinline__ void xcd_barrier(const XcdBarrier& b) {
;     ...
;             __builtin_amdgcn_fence(__ATOMIC_ACQUIRE, "agent");
;             xb_add(&bar[XB_XGEN(bx_)], 1u);
;             asm volatile("s_waitcnt vmcnt(0)" ::: "memory");
.LBB0_1500:
	s_or_b64 exec, exec, s[4:5]
	s_mov_b64 s[4:5], exec
	v_mbcnt_lo_u32_b32 v2, s4, 0
	v_mbcnt_hi_u32_b32 v2, s5, v2
	v_cmp_eq_u32_e32 vcc, 0, v2
	s_waitcnt vmcnt(0)
	buffer_inv sc1
	s_and_saveexec_b64 s[6:7], vcc
	s_cbranch_execz .LBB0_1502
	s_bcnt1_i32_b64 s4, s[4:5]
	v_mov_b32_e32 v2, s4
	v_mov_b32_e32 v4, 0x2000
.LBB0_1502:
	s_or_b64 exec, exec, s[6:7]
	s_waitcnt vmcnt(0)

; __device__ __forceinline__ unsigned xb_add(unsigned* p, unsigned v) { return __hip_atomic_fetch_add(p, v, __ATOMIC_RELAXED, __HIP_MEMORY_SCOPE_AGENT); }
; __device__ __forceinline__ void xcd_barrier(const XcdBarrier& b) {
;     ...
;             __builtin_amdgcn_fence(__ATOMIC_ACQUIRE, "agent");
;             xb_add(&bar[XB_XGEN(bx_)], 1u);
.LBB0_1813:
	s_bcnt1_i32_b64 s4, s[4:5]
	v_mov_b32_e32 v2, s4
	v_mov_b32_e32 v4, 0x2000
	s_getpc_b64 s[98:99]
